# unit heads: compiler's vmcnt(0) loop-preheader flush removed in GEMM1-3; GEMM3 prefetch loads stay in flight across first two load segments (vmcnt 17)
# baseline (speedup 1.0000x reference)
.LBB0_271:
	s_ashr_i32 s63, s62, 31
	s_lshl_b64 s[0:1], s[62:63], 20
	s_add_u32 s66, s49, s0
	s_addc_u32 s67, s82, s1
	s_and_b64 s[0:1], s[4:5], exec
	s_cselect_b32 s0, s67, s75
	s_cselect_b32 s1, s66, s74
	s_ashr_i32 s65, s64, 31
	s_lshl_b64 s[68:69], s[64:65], 20
	s_add_u32 s68, s45, s68
	s_addc_u32 s69, s47, s69
	s_and_b64 s[78:79], s[4:5], exec
	s_cselect_b32 s3, s69, s77
	s_cselect_b32 s63, s68, s76
	s_add_u32 s74, s74, 0x80080
	s_addc_u32 s75, s75, 0
	s_add_u32 s65, s76, 0x100
	s_addc_u32 s71, s77, 0
	s_mov_b32 s90, -2
	ds_read_b128 v[146:149], v166
	ds_read_b128 v[150:153], v166 offset:1024
	ds_read_b128 v[154:157], v166 offset:2048
	ds_read_b128 v[170:173], v166 offset:3072
	ds_read_b128 v[174:177], v167
	ds_read_b128 v[178:181], v167 offset:1024
	ds_read_b128 v[182:185], v167 offset:2048
	ds_read_b128 v[186:189], v167 offset:3072
	s_add_u32 s76, s74, 0xfff80080
	s_addc_u32 s77, s75, -1
	s_cmp_eq_u32 s90, 28
	s_cselect_b32 s79, s0, s77
	s_cselect_b32 s78, s1, s76
	s_cselect_b32 s77, s3, s71
	s_cselect_b32 s76, s63, s65
	s_add_i32 m0, s31, 0xc000
	ds_read_b128 v[190:193], v168
	ds_read_b128 v[194:197], v168 offset:1024
	ds_read_b128 v[198:201], v168 offset:2048
	ds_read_b128 v[202:205], v168 offset:3072
	ds_read_b128 v[206:209], v168 offset:4096
	ds_read_b128 v[214:217], v168 offset:5120
	ds_read_b128 v[218:221], v168 offset:6144
	ds_read_b128 v[222:225], v168 offset:7168
	global_load_lds_dwordx4 v138, s[74:75]
	s_add_i32 m0, s31, 0xe000
	s_nop 0
	global_load_lds_dwordx4 v140, s[74:75]
	s_waitcnt vmcnt(8)
	s_waitcnt lgkmcnt(0)
	s_setprio 1
	s_barrier
	v_mfma_f32_16x16x32_bf16 v[124:127], v[146:149], v[190:193], 0
	v_mfma_f32_16x16x32_bf16 v[120:123], v[154:157], v[190:193], 0
	v_mfma_f32_16x16x32_bf16 v[108:111], v[146:149], v[198:201], 0
	v_mfma_f32_16x16x32_bf16 v[104:107], v[154:157], v[198:201], 0
	v_mfma_f32_16x16x32_bf16 v[92:95], v[146:149], v[206:209], 0
	v_mfma_f32_16x16x32_bf16 v[88:91], v[154:157], v[206:209], 0
	v_mfma_f32_16x16x32_bf16 v[76:79], v[146:149], v[218:221], 0
	v_mfma_f32_16x16x32_bf16 v[72:75], v[154:157], v[218:221], 0
	v_mfma_f32_16x16x32_bf16 v[124:127], v[150:153], v[194:197], v[124:127]
	v_mfma_f32_16x16x32_bf16 v[120:123], v[170:173], v[194:197], v[120:123]
	v_mfma_f32_16x16x32_bf16 v[108:111], v[150:153], v[202:205], v[108:111]
	v_mfma_f32_16x16x32_bf16 v[104:107], v[170:173], v[202:205], v[104:107]
	v_mfma_f32_16x16x32_bf16 v[92:95], v[150:153], v[214:217], v[92:95]
	v_mfma_f32_16x16x32_bf16 v[88:91], v[170:173], v[214:217], v[88:91]
	v_mfma_f32_16x16x32_bf16 v[76:79], v[150:153], v[222:225], v[76:79]
	v_mfma_f32_16x16x32_bf16 v[72:75], v[170:173], v[222:225], v[72:75]
	s_setprio 0
	s_setprio 1
	v_mfma_f32_16x16x32_bf16 v[116:119], v[174:177], v[190:193], 0
	v_mfma_f32_16x16x32_bf16 v[112:115], v[182:185], v[190:193], 0
	v_mfma_f32_16x16x32_bf16 v[100:103], v[174:177], v[198:201], 0
	v_mfma_f32_16x16x32_bf16 v[96:99], v[182:185], v[198:201], 0
	v_mfma_f32_16x16x32_bf16 v[84:87], v[174:177], v[206:209], 0
	v_mfma_f32_16x16x32_bf16 v[80:83], v[182:185], v[206:209], 0
	v_mfma_f32_16x16x32_bf16 v[68:71], v[174:177], v[218:221], 0
	v_mfma_f32_16x16x32_bf16 v[64:67], v[182:185], v[218:221], 0
	v_mfma_f32_16x16x32_bf16 v[116:119], v[178:181], v[194:197], v[116:119]
	v_mfma_f32_16x16x32_bf16 v[112:115], v[186:189], v[194:197], v[112:115]
	v_mfma_f32_16x16x32_bf16 v[100:103], v[178:181], v[202:205], v[100:103]
	v_mfma_f32_16x16x32_bf16 v[96:99], v[186:189], v[202:205], v[96:99]
	v_mfma_f32_16x16x32_bf16 v[84:87], v[178:181], v[214:217], v[84:87]
	v_mfma_f32_16x16x32_bf16 v[80:83], v[186:189], v[214:217], v[80:83]
	v_mfma_f32_16x16x32_bf16 v[68:71], v[178:181], v[222:225], v[68:71]
	v_mfma_f32_16x16x32_bf16 v[64:67], v[186:189], v[222:225], v[64:67]
	s_barrier
	s_setprio 0
	s_add_i32 s91, s81, s30
	s_add_u32 s98, s76, s34
	s_addc_u32 s99, s77, s35
	s_mov_b32 m0, s91
	ds_read_b128 v[190:193], v168 offset:16384
	ds_read_b128 v[194:197], v168 offset:17408
	ds_read_b128 v[198:201], v168 offset:18432
	ds_read_b128 v[202:205], v168 offset:19456
	ds_read_b128 v[206:209], v168 offset:20480
	ds_read_b128 v[214:217], v168 offset:21504
	ds_read_b128 v[218:221], v168 offset:22528
	ds_read_b128 v[222:225], v168 offset:23552
	global_load_lds_dwordx4 v130, s[76:77]
	s_add_i32 m0, s91, 0x2000
	s_add_u32 s92, s76, 0x80000
	s_addc_u32 s93, s77, 0
	s_add_i32 s91, s83, s30
	global_load_lds_dwordx4 v134, s[76:77]
	s_mov_b32 m0, s91
	s_add_u32 s100, s78, s34
	s_addc_u32 s101, s79, s35
	global_load_lds_dwordx4 v130, s[92:93]
	s_add_i32 m0, s91, 0x2000
	s_nop 0
	global_load_lds_dwordx4 v134, s[92:93]
	s_mov_b32 m0, s31
	s_nop 0
	global_load_lds_dwordx4 v128, s[78:79]
	s_mov_b32 m0, s51
	s_nop 0
	global_load_lds_dwordx4 v132, s[78:79]
	s_waitcnt vmcnt(8)
	s_waitcnt lgkmcnt(0)
	s_setprio 1
	s_barrier
	v_mfma_f32_16x16x32_bf16 v[60:63], v[146:149], v[190:193], 0
	v_mfma_f32_16x16x32_bf16 v[56:59], v[154:157], v[190:193], 0
	v_mfma_f32_16x16x32_bf16 v[44:47], v[146:149], v[198:201], 0
	v_mfma_f32_16x16x32_bf16 v[40:43], v[154:157], v[198:201], 0
	v_mfma_f32_16x16x32_bf16 v[28:31], v[146:149], v[206:209], 0
	v_mfma_f32_16x16x32_bf16 v[24:27], v[154:157], v[206:209], 0
	v_mfma_f32_16x16x32_bf16 v[12:15], v[146:149], v[218:221], 0
	v_mfma_f32_16x16x32_bf16 v[8:11], v[154:157], v[218:221], 0
	v_mfma_f32_16x16x32_bf16 v[60:63], v[150:153], v[194:197], v[60:63]
	v_mfma_f32_16x16x32_bf16 v[56:59], v[170:173], v[194:197], v[56:59]
	v_mfma_f32_16x16x32_bf16 v[44:47], v[150:153], v[202:205], v[44:47]
	v_mfma_f32_16x16x32_bf16 v[40:43], v[170:173], v[202:205], v[40:43]
	v_mfma_f32_16x16x32_bf16 v[28:31], v[150:153], v[214:217], v[28:31]
	v_mfma_f32_16x16x32_bf16 v[24:27], v[170:173], v[214:217], v[24:27]
	v_mfma_f32_16x16x32_bf16 v[12:15], v[150:153], v[222:225], v[12:15]
	v_mfma_f32_16x16x32_bf16 v[8:11], v[170:173], v[222:225], v[8:11]
	s_setprio 0
	s_setprio 1
	v_mfma_f32_16x16x32_bf16 v[52:55], v[174:177], v[190:193], 0
	v_mfma_f32_16x16x32_bf16 v[48:51], v[182:185], v[190:193], 0
	v_mfma_f32_16x16x32_bf16 v[36:39], v[174:177], v[198:201], 0
	v_mfma_f32_16x16x32_bf16 v[32:35], v[182:185], v[198:201], 0
	v_mfma_f32_16x16x32_bf16 v[20:23], v[174:177], v[206:209], 0
	v_mfma_f32_16x16x32_bf16 v[16:19], v[182:185], v[206:209], 0
	v_mfma_f32_16x16x32_bf16 v[4:7], v[174:177], v[218:221], 0
	v_mfma_f32_16x16x32_bf16 v[0:3], v[182:185], v[218:221], 0
	v_mfma_f32_16x16x32_bf16 v[52:55], v[178:181], v[194:197], v[52:55]
	v_mfma_f32_16x16x32_bf16 v[48:51], v[186:189], v[194:197], v[48:51]
	v_mfma_f32_16x16x32_bf16 v[36:39], v[178:181], v[202:205], v[36:39]
	v_mfma_f32_16x16x32_bf16 v[32:35], v[186:189], v[202:205], v[32:35]
	v_mfma_f32_16x16x32_bf16 v[20:23], v[178:181], v[214:217], v[20:23]
	v_mfma_f32_16x16x32_bf16 v[16:19], v[186:189], v[214:217], v[16:19]
	v_mfma_f32_16x16x32_bf16 v[4:7], v[178:181], v[222:225], v[4:7]
	v_mfma_f32_16x16x32_bf16 v[0:3], v[186:189], v[222:225], v[0:3]
	s_barrier
	s_setprio 0
	s_add_i32 s91, 0, 0x18000
	v_add_u32_e32 v136, s91, v162
	s_add_i32 s92, 0, 0x1c000
	ds_read_b128 v[146:149], v136
	ds_read_b128 v[150:153], v136 offset:1024
	ds_read_b128 v[154:157], v136 offset:2048
	ds_read_b128 v[170:173], v136 offset:3072
	v_add_u32_e32 v136, s92, v162
	ds_read_b128 v[174:177], v136
	ds_read_b128 v[178:181], v136 offset:1024
	ds_read_b128 v[182:185], v136 offset:2048
	ds_read_b128 v[186:189], v136 offset:3072
	s_add_u32 s78, s78, 0x80000
	s_addc_u32 s79, s79, 0
	s_mov_b32 m0, s28
	ds_read_b128 v[190:193], v168 offset:32768
	ds_read_b128 v[194:197], v168 offset:33792
	ds_read_b128 v[198:201], v168 offset:34816
	ds_read_b128 v[202:205], v168 offset:35840
	ds_read_b128 v[206:209], v168 offset:36864
	ds_read_b128 v[214:217], v168 offset:37888
	ds_read_b128 v[218:221], v168 offset:38912
	ds_read_b128 v[222:225], v168 offset:39936
	global_load_lds_dwordx4 v128, s[78:79]
	s_mov_b32 m0, s29
	s_nop 0
	global_load_lds_dwordx4 v132, s[78:79]
	s_waitcnt vmcnt(8)
	s_waitcnt lgkmcnt(0)
	s_setprio 1
	s_barrier
	v_mfma_f32_16x16x32_bf16 v[124:127], v[146:149], v[190:193], v[124:127]
	v_mfma_f32_16x16x32_bf16 v[120:123], v[154:157], v[190:193], v[120:123]
	v_mfma_f32_16x16x32_bf16 v[108:111], v[146:149], v[198:201], v[108:111]
	v_mfma_f32_16x16x32_bf16 v[104:107], v[154:157], v[198:201], v[104:107]
	v_mfma_f32_16x16x32_bf16 v[92:95], v[146:149], v[206:209], v[92:95]
	v_mfma_f32_16x16x32_bf16 v[88:91], v[154:157], v[206:209], v[88:91]
	v_mfma_f32_16x16x32_bf16 v[76:79], v[146:149], v[218:221], v[76:79]
	v_mfma_f32_16x16x32_bf16 v[72:75], v[154:157], v[218:221], v[72:75]
	v_mfma_f32_16x16x32_bf16 v[124:127], v[150:153], v[194:197], v[124:127]
	v_mfma_f32_16x16x32_bf16 v[120:123], v[170:173], v[194:197], v[120:123]
	v_mfma_f32_16x16x32_bf16 v[108:111], v[150:153], v[202:205], v[108:111]
	v_mfma_f32_16x16x32_bf16 v[104:107], v[170:173], v[202:205], v[104:107]
	v_mfma_f32_16x16x32_bf16 v[92:95], v[150:153], v[214:217], v[92:95]
	v_mfma_f32_16x16x32_bf16 v[88:91], v[170:173], v[214:217], v[88:91]
	v_mfma_f32_16x16x32_bf16 v[76:79], v[150:153], v[222:225], v[76:79]
	v_mfma_f32_16x16x32_bf16 v[72:75], v[170:173], v[222:225], v[72:75]
	s_setprio 0
	s_setprio 1
	v_mfma_f32_16x16x32_bf16 v[116:119], v[174:177], v[190:193], v[116:119]
	v_mfma_f32_16x16x32_bf16 v[112:115], v[182:185], v[190:193], v[112:115]
	v_mfma_f32_16x16x32_bf16 v[100:103], v[174:177], v[198:201], v[100:103]
	v_mfma_f32_16x16x32_bf16 v[96:99], v[182:185], v[198:201], v[96:99]
	v_mfma_f32_16x16x32_bf16 v[84:87], v[174:177], v[206:209], v[84:87]
	v_mfma_f32_16x16x32_bf16 v[80:83], v[182:185], v[206:209], v[80:83]
	v_mfma_f32_16x16x32_bf16 v[68:71], v[174:177], v[218:221], v[68:71]
	v_mfma_f32_16x16x32_bf16 v[64:67], v[182:185], v[218:221], v[64:67]
	v_mfma_f32_16x16x32_bf16 v[116:119], v[178:181], v[194:197], v[116:119]
	v_mfma_f32_16x16x32_bf16 v[112:115], v[186:189], v[194:197], v[112:115]
	v_mfma_f32_16x16x32_bf16 v[100:103], v[178:181], v[202:205], v[100:103]
	v_mfma_f32_16x16x32_bf16 v[96:99], v[186:189], v[202:205], v[96:99]
	v_mfma_f32_16x16x32_bf16 v[84:87], v[178:181], v[214:217], v[84:87]
	v_mfma_f32_16x16x32_bf16 v[80:83], v[186:189], v[214:217], v[80:83]
	v_mfma_f32_16x16x32_bf16 v[68:71], v[178:181], v[222:225], v[68:71]
	v_mfma_f32_16x16x32_bf16 v[64:67], v[186:189], v[222:225], v[64:67]
	s_barrier
	s_setprio 0
	s_add_i32 s78, s91, s30
	s_mov_b32 m0, s78
	ds_read_b128 v[190:193], v168 offset:49152
	ds_read_b128 v[194:197], v168 offset:50176
	ds_read_b128 v[198:201], v168 offset:51200
	ds_read_b128 v[202:205], v168 offset:52224
	ds_read_b128 v[206:209], v168 offset:53248
	ds_read_b128 v[214:217], v168 offset:54272
	ds_read_b128 v[218:221], v168 offset:55296
	ds_read_b128 v[222:225], v168 offset:56320
	global_load_lds_dwordx4 v130, s[98:99]
	s_add_i32 m0, s78, 0x2000
	s_add_u32 s76, s76, 0x80080
	s_addc_u32 s77, s77, 0
	s_add_i32 s78, s92, s30
	global_load_lds_dwordx4 v134, s[98:99]
	s_mov_b32 m0, s78
	s_nop 0
	global_load_lds_dwordx4 v130, s[76:77]
	s_add_i32 m0, s78, 0x2000
	s_nop 0
	global_load_lds_dwordx4 v134, s[76:77]
	s_mov_b32 m0, s73
	s_nop 0
	global_load_lds_dwordx4 v128, s[100:101]
	s_mov_b32 m0, s80
	s_nop 0
	global_load_lds_dwordx4 v132, s[100:101]
	s_waitcnt vmcnt(8)
	s_waitcnt lgkmcnt(0)
	s_setprio 1
	s_barrier
	v_mfma_f32_16x16x32_bf16 v[60:63], v[146:149], v[190:193], v[60:63]
	v_mfma_f32_16x16x32_bf16 v[56:59], v[154:157], v[190:193], v[56:59]
	v_mfma_f32_16x16x32_bf16 v[44:47], v[146:149], v[198:201], v[44:47]
	v_mfma_f32_16x16x32_bf16 v[40:43], v[154:157], v[198:201], v[40:43]
	v_mfma_f32_16x16x32_bf16 v[28:31], v[146:149], v[206:209], v[28:31]
	v_mfma_f32_16x16x32_bf16 v[24:27], v[154:157], v[206:209], v[24:27]
	v_mfma_f32_16x16x32_bf16 v[12:15], v[146:149], v[218:221], v[12:15]
	v_mfma_f32_16x16x32_bf16 v[8:11], v[154:157], v[218:221], v[8:11]
	v_mfma_f32_16x16x32_bf16 v[60:63], v[150:153], v[194:197], v[60:63]
	v_mfma_f32_16x16x32_bf16 v[56:59], v[170:173], v[194:197], v[56:59]
	v_mfma_f32_16x16x32_bf16 v[44:47], v[150:153], v[202:205], v[44:47]
	v_mfma_f32_16x16x32_bf16 v[40:43], v[170:173], v[202:205], v[40:43]
	v_mfma_f32_16x16x32_bf16 v[28:31], v[150:153], v[214:217], v[28:31]
	v_mfma_f32_16x16x32_bf16 v[24:27], v[170:173], v[214:217], v[24:27]
	v_mfma_f32_16x16x32_bf16 v[12:15], v[150:153], v[222:225], v[12:15]
	v_mfma_f32_16x16x32_bf16 v[8:11], v[170:173], v[222:225], v[8:11]
	s_setprio 0
	s_setprio 1
	v_mfma_f32_16x16x32_bf16 v[52:55], v[174:177], v[190:193], v[52:55]
	v_mfma_f32_16x16x32_bf16 v[48:51], v[182:185], v[190:193], v[48:51]
	v_mfma_f32_16x16x32_bf16 v[36:39], v[174:177], v[198:201], v[36:39]
	v_mfma_f32_16x16x32_bf16 v[32:35], v[182:185], v[198:201], v[32:35]
	v_mfma_f32_16x16x32_bf16 v[20:23], v[174:177], v[206:209], v[20:23]
	v_mfma_f32_16x16x32_bf16 v[16:19], v[182:185], v[206:209], v[16:19]
	v_mfma_f32_16x16x32_bf16 v[4:7], v[174:177], v[218:221], v[4:7]
	v_mfma_f32_16x16x32_bf16 v[0:3], v[182:185], v[218:221], v[0:3]
	v_mfma_f32_16x16x32_bf16 v[52:55], v[178:181], v[194:197], v[52:55]
	v_mfma_f32_16x16x32_bf16 v[48:51], v[186:189], v[194:197], v[48:51]
	v_mfma_f32_16x16x32_bf16 v[36:39], v[178:181], v[202:205], v[36:39]
	v_mfma_f32_16x16x32_bf16 v[32:35], v[186:189], v[202:205], v[32:35]
	v_mfma_f32_16x16x32_bf16 v[20:23], v[178:181], v[214:217], v[20:23]
	v_mfma_f32_16x16x32_bf16 v[16:19], v[186:189], v[214:217], v[16:19]
	v_mfma_f32_16x16x32_bf16 v[4:7], v[178:181], v[222:225], v[4:7]
	v_mfma_f32_16x16x32_bf16 v[0:3], v[186:189], v[222:225], v[0:3]
	s_barrier
	s_setprio 0
	s_add_i32 s90, s90, 2
	s_add_u32 s74, s74, 0x100
	s_addc_u32 s75, s75, 0
	s_add_u32 s65, s65, 0x100
	s_addc_u32 s71, s71, 0
	s_cmp_gt_u32 s90, 29

.LBB0_542:
	s_ashr_i32 s35, s34, 31
	s_lshl_b64 s[0:1], s[34:35], 20
	s_add_u32 s36, s29, s0
	s_addc_u32 s37, s30, s1
	s_and_b64 s[0:1], s[6:7], exec
	s_cselect_b32 s0, s37, s43
	s_cselect_b32 s1, s36, s42
	s_ashr_i32 s25, s24, 31
	s_lshl_b64 s[38:39], s[24:25], 20
	s_add_u32 s38, s27, s38
	s_addc_u32 s39, s28, s39
	s_and_b64 s[46:47], s[6:7], exec
	s_cselect_b32 s3, s39, s45
	s_cselect_b32 s9, s38, s44
	s_add_u32 s42, s42, 0x80080
	s_addc_u32 s43, s43, 0
	s_add_u32 s25, s44, 0x100
	s_addc_u32 s35, s45, 0
	s_mov_b32 s58, -2
	s_waitcnt lgkmcnt(0)
	ds_read_b128 v[128:131], v216
	ds_read_b128 v[132:135], v216 offset:1024
	ds_read_b128 v[136:139], v216 offset:2048
	ds_read_b128 v[140:143], v216 offset:3072
	ds_read_b128 v[144:147], v217
	ds_read_b128 v[148:151], v217 offset:1024
	ds_read_b128 v[152:155], v217 offset:2048
	ds_read_b128 v[156:159], v217 offset:3072
	s_add_u32 s44, s42, 0xfff80080
	s_addc_u32 s45, s43, -1
	s_cmp_eq_u32 s58, 28
	s_cselect_b32 s47, s0, s45
	s_cselect_b32 s46, s1, s44
	s_cselect_b32 s45, s3, s35
	s_cselect_b32 s44, s9, s25
	s_add_i32 m0, s41, 0xc000
	ds_read_b128 v[160:163], v218
	ds_read_b128 v[164:167], v218 offset:1024
	ds_read_b128 v[168:171], v218 offset:2048
	ds_read_b128 v[172:175], v218 offset:3072
	ds_read_b128 v[192:195], v218 offset:4096
	ds_read_b128 v[196:199], v218 offset:5120
	ds_read_b128 v[200:203], v218 offset:6144
	ds_read_b128 v[204:207], v218 offset:7168
	global_load_lds_dwordx4 v184, s[42:43]
	s_add_i32 m0, s41, 0xe000
	s_nop 0
	global_load_lds_dwordx4 v186, s[42:43]
	s_waitcnt vmcnt(8)
	s_waitcnt lgkmcnt(0)
	s_setprio 1
	s_barrier
	v_mfma_f32_16x16x32_bf16 v[124:127], v[128:131], v[160:163], 0
	v_mfma_f32_16x16x32_bf16 v[120:123], v[136:139], v[160:163], 0
	v_mfma_f32_16x16x32_bf16 v[108:111], v[128:131], v[168:171], 0
	v_mfma_f32_16x16x32_bf16 v[104:107], v[136:139], v[168:171], 0
	v_mfma_f32_16x16x32_bf16 v[92:95], v[128:131], v[192:195], 0
	v_mfma_f32_16x16x32_bf16 v[88:91], v[136:139], v[192:195], 0
	v_mfma_f32_16x16x32_bf16 v[76:79], v[128:131], v[200:203], 0
	v_mfma_f32_16x16x32_bf16 v[72:75], v[136:139], v[200:203], 0
	v_mfma_f32_16x16x32_bf16 v[124:127], v[132:135], v[164:167], v[124:127]
	v_mfma_f32_16x16x32_bf16 v[120:123], v[140:143], v[164:167], v[120:123]
	v_mfma_f32_16x16x32_bf16 v[108:111], v[132:135], v[172:175], v[108:111]
	v_mfma_f32_16x16x32_bf16 v[104:107], v[140:143], v[172:175], v[104:107]
	v_mfma_f32_16x16x32_bf16 v[92:95], v[132:135], v[196:199], v[92:95]
	v_mfma_f32_16x16x32_bf16 v[88:91], v[140:143], v[196:199], v[88:91]
	v_mfma_f32_16x16x32_bf16 v[76:79], v[132:135], v[204:207], v[76:79]
	v_mfma_f32_16x16x32_bf16 v[72:75], v[140:143], v[204:207], v[72:75]
	s_setprio 0
	s_setprio 1
	v_mfma_f32_16x16x32_bf16 v[116:119], v[144:147], v[160:163], 0
	v_mfma_f32_16x16x32_bf16 v[112:115], v[152:155], v[160:163], 0
	v_mfma_f32_16x16x32_bf16 v[100:103], v[144:147], v[168:171], 0
	v_mfma_f32_16x16x32_bf16 v[96:99], v[152:155], v[168:171], 0
	v_mfma_f32_16x16x32_bf16 v[84:87], v[144:147], v[192:195], 0
	v_mfma_f32_16x16x32_bf16 v[80:83], v[152:155], v[192:195], 0
	v_mfma_f32_16x16x32_bf16 v[68:71], v[144:147], v[200:203], 0
	v_mfma_f32_16x16x32_bf16 v[64:67], v[152:155], v[200:203], 0
	v_mfma_f32_16x16x32_bf16 v[116:119], v[148:151], v[164:167], v[116:119]
	v_mfma_f32_16x16x32_bf16 v[112:115], v[156:159], v[164:167], v[112:115]
	v_mfma_f32_16x16x32_bf16 v[100:103], v[148:151], v[172:175], v[100:103]
	v_mfma_f32_16x16x32_bf16 v[96:99], v[156:159], v[172:175], v[96:99]
	v_mfma_f32_16x16x32_bf16 v[84:87], v[148:151], v[196:199], v[84:87]
	v_mfma_f32_16x16x32_bf16 v[80:83], v[156:159], v[196:199], v[80:83]
	v_mfma_f32_16x16x32_bf16 v[68:71], v[148:151], v[204:207], v[68:71]
	v_mfma_f32_16x16x32_bf16 v[64:67], v[156:159], v[204:207], v[64:67]
	s_barrier
	s_setprio 0
	s_add_i32 s59, s55, s31
	s_add_u32 s98, s44, s20
	s_addc_u32 s99, s45, s21
	s_mov_b32 m0, s59
	ds_read_b128 v[160:163], v218 offset:16384
	ds_read_b128 v[164:167], v218 offset:17408
	ds_read_b128 v[168:171], v218 offset:18432
	ds_read_b128 v[172:175], v218 offset:19456
	ds_read_b128 v[192:195], v218 offset:20480
	ds_read_b128 v[196:199], v218 offset:21504
	ds_read_b128 v[200:203], v218 offset:22528
	ds_read_b128 v[204:207], v218 offset:23552
	global_load_lds_dwordx4 v178, s[44:45]
	s_add_i32 m0, s59, 0x2000
	s_add_u32 s60, s44, 0x80000
	s_addc_u32 s61, s45, 0
	s_add_i32 s59, s56, s31
	global_load_lds_dwordx4 v182, s[44:45]
	s_mov_b32 m0, s59
	s_add_u32 s100, s46, s20
	s_addc_u32 s101, s47, s21
	global_load_lds_dwordx4 v178, s[60:61]
	s_add_i32 m0, s59, 0x2000
	s_nop 0
	global_load_lds_dwordx4 v182, s[60:61]
	s_mov_b32 m0, s41
	s_nop 0
	global_load_lds_dwordx4 v176, s[46:47]
	s_mov_b32 m0, s48
	s_nop 0
	global_load_lds_dwordx4 v180, s[46:47]
	s_waitcnt vmcnt(8)
	s_waitcnt lgkmcnt(0)
	s_setprio 1
	s_barrier
	v_mfma_f32_16x16x32_bf16 v[60:63], v[128:131], v[160:163], 0
	v_mfma_f32_16x16x32_bf16 v[56:59], v[136:139], v[160:163], 0
	v_mfma_f32_16x16x32_bf16 v[44:47], v[128:131], v[168:171], 0
	v_mfma_f32_16x16x32_bf16 v[40:43], v[136:139], v[168:171], 0
	v_mfma_f32_16x16x32_bf16 v[28:31], v[128:131], v[192:195], 0
	v_mfma_f32_16x16x32_bf16 v[24:27], v[136:139], v[192:195], 0
	v_mfma_f32_16x16x32_bf16 v[12:15], v[128:131], v[200:203], 0
	v_mfma_f32_16x16x32_bf16 v[8:11], v[136:139], v[200:203], 0
	v_mfma_f32_16x16x32_bf16 v[60:63], v[132:135], v[164:167], v[60:63]
	v_mfma_f32_16x16x32_bf16 v[56:59], v[140:143], v[164:167], v[56:59]
	v_mfma_f32_16x16x32_bf16 v[44:47], v[132:135], v[172:175], v[44:47]
	v_mfma_f32_16x16x32_bf16 v[40:43], v[140:143], v[172:175], v[40:43]
	v_mfma_f32_16x16x32_bf16 v[28:31], v[132:135], v[196:199], v[28:31]
	v_mfma_f32_16x16x32_bf16 v[24:27], v[140:143], v[196:199], v[24:27]
	v_mfma_f32_16x16x32_bf16 v[12:15], v[132:135], v[204:207], v[12:15]
	v_mfma_f32_16x16x32_bf16 v[8:11], v[140:143], v[204:207], v[8:11]
	s_setprio 0
	s_setprio 1
	v_mfma_f32_16x16x32_bf16 v[52:55], v[144:147], v[160:163], 0
	v_mfma_f32_16x16x32_bf16 v[48:51], v[152:155], v[160:163], 0
	v_mfma_f32_16x16x32_bf16 v[36:39], v[144:147], v[168:171], 0
	v_mfma_f32_16x16x32_bf16 v[32:35], v[152:155], v[168:171], 0
	v_mfma_f32_16x16x32_bf16 v[20:23], v[144:147], v[192:195], 0
	v_mfma_f32_16x16x32_bf16 v[16:19], v[152:155], v[192:195], 0
	v_mfma_f32_16x16x32_bf16 v[4:7], v[144:147], v[200:203], 0
	v_mfma_f32_16x16x32_bf16 v[0:3], v[152:155], v[200:203], 0
	v_mfma_f32_16x16x32_bf16 v[52:55], v[148:151], v[164:167], v[52:55]
	v_mfma_f32_16x16x32_bf16 v[48:51], v[156:159], v[164:167], v[48:51]
	v_mfma_f32_16x16x32_bf16 v[36:39], v[148:151], v[172:175], v[36:39]
	v_mfma_f32_16x16x32_bf16 v[32:35], v[156:159], v[172:175], v[32:35]
	v_mfma_f32_16x16x32_bf16 v[20:23], v[148:151], v[196:199], v[20:23]
	v_mfma_f32_16x16x32_bf16 v[16:19], v[156:159], v[196:199], v[16:19]
	v_mfma_f32_16x16x32_bf16 v[4:7], v[148:151], v[204:207], v[4:7]
	v_mfma_f32_16x16x32_bf16 v[0:3], v[156:159], v[204:207], v[0:3]
	s_barrier
	s_setprio 0
	s_add_i32 s59, 0, 0x18000
	s_add_i32 s60, 0, 0x1c000
	v_add_u32_e32 v140, s59, v214
	v_add_u32_e32 v156, s60, v214
	ds_read_b128 v[128:131], v140
	ds_read_b128 v[132:135], v140 offset:1024
	ds_read_b128 v[136:139], v140 offset:2048
	ds_read_b128 v[140:143], v140 offset:3072
	ds_read_b128 v[144:147], v156
	ds_read_b128 v[148:151], v156 offset:1024
	ds_read_b128 v[152:155], v156 offset:2048
	ds_read_b128 v[156:159], v156 offset:3072
	s_add_u32 s46, s46, 0x80000
	s_addc_u32 s47, s47, 0
	s_mov_b32 m0, s49
	ds_read_b128 v[160:163], v218 offset:32768
	ds_read_b128 v[164:167], v218 offset:33792
	ds_read_b128 v[168:171], v218 offset:34816
	ds_read_b128 v[172:175], v218 offset:35840
	ds_read_b128 v[192:195], v218 offset:36864
	ds_read_b128 v[196:199], v218 offset:37888
	ds_read_b128 v[200:203], v218 offset:38912
	ds_read_b128 v[204:207], v218 offset:39936
	global_load_lds_dwordx4 v176, s[46:47]
	s_mov_b32 m0, s50
	s_nop 0
	global_load_lds_dwordx4 v180, s[46:47]
	s_waitcnt vmcnt(8)
	s_waitcnt lgkmcnt(0)
	s_setprio 1
	s_barrier
	v_mfma_f32_16x16x32_bf16 v[124:127], v[128:131], v[160:163], v[124:127]
	v_mfma_f32_16x16x32_bf16 v[120:123], v[136:139], v[160:163], v[120:123]
	v_mfma_f32_16x16x32_bf16 v[108:111], v[128:131], v[168:171], v[108:111]
	v_mfma_f32_16x16x32_bf16 v[104:107], v[136:139], v[168:171], v[104:107]
	v_mfma_f32_16x16x32_bf16 v[92:95], v[128:131], v[192:195], v[92:95]
	v_mfma_f32_16x16x32_bf16 v[88:91], v[136:139], v[192:195], v[88:91]
	v_mfma_f32_16x16x32_bf16 v[76:79], v[128:131], v[200:203], v[76:79]
	v_mfma_f32_16x16x32_bf16 v[72:75], v[136:139], v[200:203], v[72:75]
	v_mfma_f32_16x16x32_bf16 v[124:127], v[132:135], v[164:167], v[124:127]
	v_mfma_f32_16x16x32_bf16 v[120:123], v[140:143], v[164:167], v[120:123]
	v_mfma_f32_16x16x32_bf16 v[108:111], v[132:135], v[172:175], v[108:111]
	v_mfma_f32_16x16x32_bf16 v[104:107], v[140:143], v[172:175], v[104:107]
	v_mfma_f32_16x16x32_bf16 v[92:95], v[132:135], v[196:199], v[92:95]
	v_mfma_f32_16x16x32_bf16 v[88:91], v[140:143], v[196:199], v[88:91]
	v_mfma_f32_16x16x32_bf16 v[76:79], v[132:135], v[204:207], v[76:79]
	v_mfma_f32_16x16x32_bf16 v[72:75], v[140:143], v[204:207], v[72:75]
	s_setprio 0
	s_setprio 1
	v_mfma_f32_16x16x32_bf16 v[116:119], v[144:147], v[160:163], v[116:119]
	v_mfma_f32_16x16x32_bf16 v[112:115], v[152:155], v[160:163], v[112:115]
	v_mfma_f32_16x16x32_bf16 v[100:103], v[144:147], v[168:171], v[100:103]
	v_mfma_f32_16x16x32_bf16 v[96:99], v[152:155], v[168:171], v[96:99]
	v_mfma_f32_16x16x32_bf16 v[84:87], v[144:147], v[192:195], v[84:87]
	v_mfma_f32_16x16x32_bf16 v[80:83], v[152:155], v[192:195], v[80:83]
	v_mfma_f32_16x16x32_bf16 v[68:71], v[144:147], v[200:203], v[68:71]
	v_mfma_f32_16x16x32_bf16 v[64:67], v[152:155], v[200:203], v[64:67]
	v_mfma_f32_16x16x32_bf16 v[116:119], v[148:151], v[164:167], v[116:119]
	v_mfma_f32_16x16x32_bf16 v[112:115], v[156:159], v[164:167], v[112:115]
	v_mfma_f32_16x16x32_bf16 v[100:103], v[148:151], v[172:175], v[100:103]
	v_mfma_f32_16x16x32_bf16 v[96:99], v[156:159], v[172:175], v[96:99]
	v_mfma_f32_16x16x32_bf16 v[84:87], v[148:151], v[196:199], v[84:87]
	v_mfma_f32_16x16x32_bf16 v[80:83], v[156:159], v[196:199], v[80:83]
	v_mfma_f32_16x16x32_bf16 v[68:71], v[148:151], v[204:207], v[68:71]
	v_mfma_f32_16x16x32_bf16 v[64:67], v[156:159], v[204:207], v[64:67]
	s_barrier
	s_setprio 0
	s_add_i32 s46, s59, s31
	s_mov_b32 m0, s46
	ds_read_b128 v[160:163], v218 offset:49152
	ds_read_b128 v[164:167], v218 offset:50176
	ds_read_b128 v[168:171], v218 offset:51200
	ds_read_b128 v[172:175], v218 offset:52224
	ds_read_b128 v[192:195], v218 offset:53248
	ds_read_b128 v[196:199], v218 offset:54272
	ds_read_b128 v[200:203], v218 offset:55296
	ds_read_b128 v[204:207], v218 offset:56320
	global_load_lds_dwordx4 v178, s[98:99]
	s_add_i32 m0, s46, 0x2000
	s_add_u32 s44, s44, 0x80080
	s_addc_u32 s45, s45, 0
	s_add_i32 s46, s60, s31
	global_load_lds_dwordx4 v182, s[98:99]
	s_mov_b32 m0, s46
	s_nop 0
	global_load_lds_dwordx4 v178, s[44:45]
	s_add_i32 m0, s46, 0x2000
	s_nop 0
	global_load_lds_dwordx4 v182, s[44:45]
	s_mov_b32 m0, s52
	s_nop 0
	global_load_lds_dwordx4 v176, s[100:101]
	s_mov_b32 m0, s53
	s_nop 0
	global_load_lds_dwordx4 v180, s[100:101]
	s_waitcnt vmcnt(8)
	s_waitcnt lgkmcnt(0)
	s_setprio 1
	s_barrier
	v_mfma_f32_16x16x32_bf16 v[60:63], v[128:131], v[160:163], v[60:63]
	v_mfma_f32_16x16x32_bf16 v[56:59], v[136:139], v[160:163], v[56:59]
	v_mfma_f32_16x16x32_bf16 v[44:47], v[128:131], v[168:171], v[44:47]
	v_mfma_f32_16x16x32_bf16 v[40:43], v[136:139], v[168:171], v[40:43]
	v_mfma_f32_16x16x32_bf16 v[28:31], v[128:131], v[192:195], v[28:31]
	v_mfma_f32_16x16x32_bf16 v[24:27], v[136:139], v[192:195], v[24:27]
	v_mfma_f32_16x16x32_bf16 v[12:15], v[128:131], v[200:203], v[12:15]
	v_mfma_f32_16x16x32_bf16 v[8:11], v[136:139], v[200:203], v[8:11]
	v_mfma_f32_16x16x32_bf16 v[60:63], v[132:135], v[164:167], v[60:63]
	v_mfma_f32_16x16x32_bf16 v[56:59], v[140:143], v[164:167], v[56:59]
	v_mfma_f32_16x16x32_bf16 v[44:47], v[132:135], v[172:175], v[44:47]
	v_mfma_f32_16x16x32_bf16 v[40:43], v[140:143], v[172:175], v[40:43]
	v_mfma_f32_16x16x32_bf16 v[28:31], v[132:135], v[196:199], v[28:31]
	v_mfma_f32_16x16x32_bf16 v[24:27], v[140:143], v[196:199], v[24:27]
	v_mfma_f32_16x16x32_bf16 v[12:15], v[132:135], v[204:207], v[12:15]
	v_mfma_f32_16x16x32_bf16 v[8:11], v[140:143], v[204:207], v[8:11]
	s_setprio 0
	s_setprio 1
	v_mfma_f32_16x16x32_bf16 v[52:55], v[144:147], v[160:163], v[52:55]
	v_mfma_f32_16x16x32_bf16 v[48:51], v[152:155], v[160:163], v[48:51]
	v_mfma_f32_16x16x32_bf16 v[36:39], v[144:147], v[168:171], v[36:39]
	v_mfma_f32_16x16x32_bf16 v[32:35], v[152:155], v[168:171], v[32:35]
	v_mfma_f32_16x16x32_bf16 v[20:23], v[144:147], v[192:195], v[20:23]
	v_mfma_f32_16x16x32_bf16 v[16:19], v[152:155], v[192:195], v[16:19]
	v_mfma_f32_16x16x32_bf16 v[4:7], v[144:147], v[200:203], v[4:7]
	v_mfma_f32_16x16x32_bf16 v[0:3], v[152:155], v[200:203], v[0:3]
	v_mfma_f32_16x16x32_bf16 v[52:55], v[148:151], v[164:167], v[52:55]
	v_mfma_f32_16x16x32_bf16 v[48:51], v[156:159], v[164:167], v[48:51]
	v_mfma_f32_16x16x32_bf16 v[36:39], v[148:151], v[172:175], v[36:39]
	v_mfma_f32_16x16x32_bf16 v[32:35], v[156:159], v[172:175], v[32:35]
	v_mfma_f32_16x16x32_bf16 v[20:23], v[148:151], v[196:199], v[20:23]
	v_mfma_f32_16x16x32_bf16 v[16:19], v[156:159], v[196:199], v[16:19]
	v_mfma_f32_16x16x32_bf16 v[4:7], v[148:151], v[204:207], v[4:7]
	v_mfma_f32_16x16x32_bf16 v[0:3], v[156:159], v[204:207], v[0:3]
	s_barrier
	s_setprio 0
	s_add_i32 s58, s58, 2
	s_add_u32 s42, s42, 0x100
	s_addc_u32 s43, s43, 0
	s_add_u32 s25, s25, 0x100
	s_addc_u32 s35, s35, 0
	s_cmp_gt_u32 s58, 29

.LBB0_624:
	s_add_u32 s38, s12, 0x6000000
	s_mov_b64 s[40:41], 0x80
	s_addc_u32 s39, s13, 0
	s_add_i32 m0, s72, 0x18000
	v_lshl_add_u64 v[8:9], v[8:9], 0, s[40:41]
	s_lshl_b32 s12, s3, 13
	s_lshl_b32 s79, s1, 5
	s_lshl_b32 s13, s1, 12
	s_waitcnt vmcnt(2)
	s_barrier
	global_load_lds_dwordx4 v[8:9], off
	v_lshl_add_u64 v[6:7], v[6:7], 0, s[40:41]
	s_add_i32 m0, s72, 0x1a000
	s_add_i32 s82, s72, 0x8000
	s_add_i32 s83, s72, 0xa000
	global_load_lds_dwordx4 v[6:7], off
	v_lshl_add_u64 v[4:5], v[4:5], 0, s[40:41]
	s_mov_b32 m0, s82
	s_add_u32 s6, s10, 0x80080
	global_load_lds_dwordx4 v[4:5], off
	v_lshl_add_u64 v[2:3], v[2:3], 0, s[40:41]
	s_mov_b32 m0, s83
	s_addc_u32 s7, s11, 0
	global_load_lds_dwordx4 v[2:3], off
	s_add_i32 m0, s72, 0x1c000
	v_lshl_add_u64 v[2:3], s[6:7], 0, v[154:155]
	global_load_lds_dwordx4 v[2:3], off
	v_lshl_add_u64 v[2:3], s[6:7], 0, v[158:159]
	s_add_i32 m0, s72, 0x1e000
	s_movk_i32 s6, 0x3c0
	global_load_lds_dwordx4 v[2:3], off
	v_lshlrev_b32_e32 v2, 4, v193
	v_lshlrev_b32_e32 v3, 6, v1
	v_lshlrev_b32_e32 v1, 2, v1
	v_and_or_b32 v3, v3, s6, v2
	v_and_b32_e32 v1, 32, v1
	v_bitop3_b32 v3, v3, s12, v1 bitop3:0xde
	v_lshl_or_b32 v1, v192, 6, v2
	v_lshlrev_b32_e32 v2, 2, v192
	v_and_b32_e32 v2, 32, v2
	v_bitop3_b32 v196, v1, s13, v2 bitop3:0xde
	s_cmpk_lt_u32 s0, 0x100
	v_mov_b32_e32 v1, v155
	s_cselect_b64 s[42:43], -1, 0
	s_and_b32 s0, s0, 0xffffff00
	s_lshl_b32 s1, s1, 6
	s_lshl_b32 s85, s3, 7
	v_lshl_add_u64 v[160:161], s[4:5], 0, v[0:1]
	v_lshlrev_b32_e32 v0, 15, v10
	s_or_b32 s84, s1, s0
	s_add_i32 s0, s85, 0x100
	v_and_b32_e32 v0, 0xffff0000, v0
	s_cmp_gt_i32 s3, 0
	v_lshl_add_u32 v0, v11, 12, v0
	v_and_b32_e32 v1, 1, v10
	s_cselect_b64 s[44:45], -1, 0
	s_cmp_lt_i32 s3, 3
	v_lshl_or_b32 v0, v1, 6, v0
	s_cselect_b64 s[46:47], -1, 0
	s_lshl_b32 s1, s3, 9
	s_add_i32 s86, s65, 0x80
	v_lshl_add_u32 v162, v12, 1, v0
	v_lshlrev_b32_e32 v0, 15, v13
	s_cmp_gt_i32 s3, -2
	v_and_b32_e32 v0, 0xffff0000, v0
	s_waitcnt vmcnt(0)
	s_cselect_b64 s[48:49], -1, 0
	s_cmp_lt_i32 s3, 1
	v_lshl_add_u32 v0, v14, 12, v0
	v_and_b32_e32 v1, 1, v13
	s_cselect_b64 s[50:51], -1, 0
	s_add_i32 s87, s1, 0x400
	s_add_i32 s89, 0, 0x20000
	s_add_i32 s93, 0, 0x20600
	v_lshl_or_b32 v0, v1, 6, v0
	s_add_i32 s94, 0, 0x10000
	s_add_i32 s95, 0, 0x14000
	s_ashr_i32 s88, s53, 31
	s_add_i32 s90, s89, s1
	s_add_i32 s91, s93, s1
	s_add_i32 s92, s89, s87
	s_add_i32 s93, s93, s87
	v_mov_b32_e32 v163, v155
	v_lshl_add_u32 v164, v15, 1, v0
	v_mov_b32_e32 v165, v155
	v_mov_b64_e32 v[166:167], 0xaeb
	v_mov_b64_e32 v[168:169], 0xaea
	v_add_u32_e32 v197, s94, v196
	v_add_u32_e32 v198, s95, v196
	v_add_u32_e32 v199, 0, v3
	s_add_i32 s96, 0, 0x21400
	v_mov_b32_e32 v200, 0x358637bd
	s_add_i32 s97, 0, 0x20800
	s_lshl_b32 s0, s0, 2
	s_mov_b32 s52, 0x3e6d3388
	s_mov_b32 s54, 0x3f07dc22
	s_mov_b32 s56, 0xbf3a00e3
	v_mov_b32_e32 v246, s56
	s_mov_b32 s58, 0x3f35f0e3
	s_mov_b32 s60, 0xbe11a98e
	s_mov_b32 s62, 0x3e027906
	s_mov_b32 s64, 0xbf38aa3b
	s_movk_i32 s31, 0x2b00
	s_movk_i32 s80, 0x1fff
	s_movk_i32 s81, 0x1ff0
	s_movk_i32 s26, 0x1fe0
	s_movk_i32 s27, 0x1fd0
	s_barrier
	s_branch .LBB0_627

.LBB0_635:
	s_ashr_i32 s67, s66, 31
	s_lshl_b64 s[12:13], s[66:67], 20
	s_add_u32 s70, s55, s12
	s_addc_u32 s71, s57, s13
	s_and_b64 s[6:7], s[6:7], exec
	s_cselect_b32 s1, s71, s11
	s_cselect_b32 s3, s70, s10
	s_add_u32 s6, s8, 0x80080
	s_addc_u32 s7, s9, 0
	s_add_u32 s12, s10, 0x100
	s_addc_u32 s13, s11, 0
	s_mov_b32 s15, -2
	ds_read_b128 v[148:151], v197
	ds_read_b128 v[170:173], v197 offset:1024
	ds_read_b128 v[174:177], v197 offset:2048
	ds_read_b128 v[178:181], v197 offset:3072
	ds_read_b128 v[182:185], v198
	ds_read_b128 v[186:189], v198 offset:1024
	ds_read_b128 v[202:205], v198 offset:2048
	ds_read_b128 v[206:209], v198 offset:3072
	s_add_u32 s8, s6, 0xfff80080
	s_addc_u32 s9, s7, -1
	s_cmp_eq_u32 s15, 28
	s_cselect_b32 s11, s69, s9
	s_cselect_b32 s10, s68, s8
	s_cselect_b32 s9, s1, s13
	s_cselect_b32 s8, s3, s12
	s_add_i32 m0, s72, 0xc000
	ds_read_b128 v[214:217], v199
	ds_read_b128 v[218:221], v199 offset:1024
	ds_read_b128 v[222:225], v199 offset:2048
	ds_read_b128 v[226:229], v199 offset:3072
	ds_read_b128 v[230:233], v199 offset:4096
	ds_read_b128 v[234:237], v199 offset:5120
	ds_read_b128 v[238:241], v199 offset:6144
	ds_read_b128 v[242:245], v199 offset:7168
	global_load_lds_dwordx4 v162, s[6:7]
	s_add_i32 m0, s72, 0xe000
	s_nop 0
	global_load_lds_dwordx4 v164, s[6:7]
	s_waitcnt vmcnt(17)
	s_waitcnt lgkmcnt(0)
	s_setprio 1
	s_barrier
	v_mfma_f32_16x16x32_bf16 v[112:115], v[148:151], v[214:217], 0
	v_mfma_f32_16x16x32_bf16 v[80:83], v[174:177], v[214:217], 0
	v_mfma_f32_16x16x32_bf16 v[116:119], v[148:151], v[222:225], 0
	v_mfma_f32_16x16x32_bf16 v[88:91], v[174:177], v[222:225], 0
	v_mfma_f32_16x16x32_bf16 v[124:127], v[148:151], v[230:233], 0
	v_mfma_f32_16x16x32_bf16 v[92:95], v[174:177], v[230:233], 0
	v_mfma_f32_16x16x32_bf16 v[120:123], v[148:151], v[238:241], 0
	v_mfma_f32_16x16x32_bf16 v[84:87], v[174:177], v[238:241], 0
	v_mfma_f32_16x16x32_bf16 v[112:115], v[170:173], v[218:221], v[112:115]
	v_mfma_f32_16x16x32_bf16 v[80:83], v[178:181], v[218:221], v[80:83]
	v_mfma_f32_16x16x32_bf16 v[116:119], v[170:173], v[226:229], v[116:119]
	v_mfma_f32_16x16x32_bf16 v[88:91], v[178:181], v[226:229], v[88:91]
	v_mfma_f32_16x16x32_bf16 v[124:127], v[170:173], v[234:237], v[124:127]
	v_mfma_f32_16x16x32_bf16 v[92:95], v[178:181], v[234:237], v[92:95]
	v_mfma_f32_16x16x32_bf16 v[120:123], v[170:173], v[242:245], v[120:123]
	v_mfma_f32_16x16x32_bf16 v[84:87], v[178:181], v[242:245], v[84:87]
	s_setprio 0
	s_setprio 1
	v_mfma_f32_16x16x32_bf16 v[108:111], v[182:185], v[214:217], 0
	v_mfma_f32_16x16x32_bf16 v[76:79], v[202:205], v[214:217], 0
	v_mfma_f32_16x16x32_bf16 v[104:107], v[182:185], v[222:225], 0
	v_mfma_f32_16x16x32_bf16 v[72:75], v[202:205], v[222:225], 0
	v_mfma_f32_16x16x32_bf16 v[100:103], v[182:185], v[230:233], 0
	v_mfma_f32_16x16x32_bf16 v[68:71], v[202:205], v[230:233], 0
	v_mfma_f32_16x16x32_bf16 v[96:99], v[182:185], v[238:241], 0
	v_mfma_f32_16x16x32_bf16 v[64:67], v[202:205], v[238:241], 0
	v_mfma_f32_16x16x32_bf16 v[108:111], v[186:189], v[218:221], v[108:111]
	v_mfma_f32_16x16x32_bf16 v[76:79], v[206:209], v[218:221], v[76:79]
	v_mfma_f32_16x16x32_bf16 v[104:107], v[186:189], v[226:229], v[104:107]
	v_mfma_f32_16x16x32_bf16 v[72:75], v[206:209], v[226:229], v[72:75]
	v_mfma_f32_16x16x32_bf16 v[100:103], v[186:189], v[234:237], v[100:103]
	v_mfma_f32_16x16x32_bf16 v[68:71], v[206:209], v[234:237], v[68:71]
	v_mfma_f32_16x16x32_bf16 v[96:99], v[186:189], v[242:245], v[96:99]
	v_mfma_f32_16x16x32_bf16 v[64:67], v[206:209], v[242:245], v[64:67]
	s_barrier
	s_setprio 0
	s_add_i32 s16, s94, s63
	s_add_u32 s98, s8, s40
	s_addc_u32 s99, s9, s41
	s_mov_b32 m0, s16
	ds_read_b128 v[214:217], v199 offset:16384
	ds_read_b128 v[218:221], v199 offset:17408
	ds_read_b128 v[222:225], v199 offset:18432
	ds_read_b128 v[226:229], v199 offset:19456
	ds_read_b128 v[230:233], v199 offset:20480
	ds_read_b128 v[234:237], v199 offset:21504
	ds_read_b128 v[238:241], v199 offset:22528
	ds_read_b128 v[242:245], v199 offset:23552
	global_load_lds_dwordx4 v154, s[8:9]
	s_add_i32 m0, s16, 0x2000
	s_add_u32 s16, s8, 0x80000
	s_addc_u32 s17, s9, 0
	s_add_i32 s18, s95, s63
	global_load_lds_dwordx4 v158, s[8:9]
	s_mov_b32 m0, s18
	s_add_u32 s100, s10, s40
	s_addc_u32 s101, s11, s41
	global_load_lds_dwordx4 v154, s[16:17]
	s_add_i32 m0, s18, 0x2000
	s_nop 0
	global_load_lds_dwordx4 v158, s[16:17]
	s_mov_b32 m0, s72
	s_nop 0
	global_load_lds_dwordx4 v152, s[10:11]
	s_mov_b32 m0, s73
	s_nop 0
	global_load_lds_dwordx4 v156, s[10:11]
	s_waitcnt vmcnt(17)
	s_waitcnt lgkmcnt(0)
	s_setprio 1
	s_barrier
	v_mfma_f32_16x16x32_bf16 v[48:51], v[148:151], v[214:217], 0
	v_mfma_f32_16x16x32_bf16 v[16:19], v[174:177], v[214:217], 0
	v_mfma_f32_16x16x32_bf16 v[52:55], v[148:151], v[222:225], 0
	v_mfma_f32_16x16x32_bf16 v[24:27], v[174:177], v[222:225], 0
	v_mfma_f32_16x16x32_bf16 v[60:63], v[148:151], v[230:233], 0
	v_mfma_f32_16x16x32_bf16 v[28:31], v[174:177], v[230:233], 0
	v_mfma_f32_16x16x32_bf16 v[56:59], v[148:151], v[238:241], 0
	v_mfma_f32_16x16x32_bf16 v[20:23], v[174:177], v[238:241], 0
	v_mfma_f32_16x16x32_bf16 v[48:51], v[170:173], v[218:221], v[48:51]
	v_mfma_f32_16x16x32_bf16 v[16:19], v[178:181], v[218:221], v[16:19]
	v_mfma_f32_16x16x32_bf16 v[52:55], v[170:173], v[226:229], v[52:55]
	v_mfma_f32_16x16x32_bf16 v[24:27], v[178:181], v[226:229], v[24:27]
	v_mfma_f32_16x16x32_bf16 v[60:63], v[170:173], v[234:237], v[60:63]
	v_mfma_f32_16x16x32_bf16 v[28:31], v[178:181], v[234:237], v[28:31]
	v_mfma_f32_16x16x32_bf16 v[56:59], v[170:173], v[242:245], v[56:59]
	v_mfma_f32_16x16x32_bf16 v[20:23], v[178:181], v[242:245], v[20:23]
	s_setprio 0
	s_setprio 1
	v_mfma_f32_16x16x32_bf16 v[44:47], v[182:185], v[214:217], 0
	v_mfma_f32_16x16x32_bf16 v[12:15], v[202:205], v[214:217], 0
	v_mfma_f32_16x16x32_bf16 v[40:43], v[182:185], v[222:225], 0
	v_mfma_f32_16x16x32_bf16 v[8:11], v[202:205], v[222:225], 0
	v_mfma_f32_16x16x32_bf16 v[36:39], v[182:185], v[230:233], 0
	v_mfma_f32_16x16x32_bf16 v[4:7], v[202:205], v[230:233], 0
	v_mfma_f32_16x16x32_bf16 v[32:35], v[182:185], v[238:241], 0
	v_mfma_f32_16x16x32_bf16 v[0:3], v[202:205], v[238:241], 0
	v_mfma_f32_16x16x32_bf16 v[44:47], v[186:189], v[218:221], v[44:47]
	v_mfma_f32_16x16x32_bf16 v[12:15], v[206:209], v[218:221], v[12:15]
	v_mfma_f32_16x16x32_bf16 v[40:43], v[186:189], v[226:229], v[40:43]
	v_mfma_f32_16x16x32_bf16 v[8:11], v[206:209], v[226:229], v[8:11]
	v_mfma_f32_16x16x32_bf16 v[36:39], v[186:189], v[234:237], v[36:39]
	v_mfma_f32_16x16x32_bf16 v[4:7], v[206:209], v[234:237], v[4:7]
	v_mfma_f32_16x16x32_bf16 v[32:35], v[186:189], v[242:245], v[32:35]
	v_mfma_f32_16x16x32_bf16 v[0:3], v[206:209], v[242:245], v[0:3]
	s_barrier
	s_setprio 0
	s_add_i32 s16, 0, 0x18000
	s_add_i32 s17, 0, 0x1c000
	v_add_u32_e32 v178, s16, v196
	v_add_u32_e32 v201, s17, v196
	ds_read_b128 v[148:151], v178
	ds_read_b128 v[170:173], v178 offset:1024
	ds_read_b128 v[174:177], v178 offset:2048
	ds_read_b128 v[178:181], v178 offset:3072
	ds_read_b128 v[182:185], v201
	ds_read_b128 v[186:189], v201 offset:1024
	ds_read_b128 v[202:205], v201 offset:2048
	ds_read_b128 v[206:209], v201 offset:3072
	s_add_u32 s10, s10, 0x80000
	s_addc_u32 s11, s11, 0
	s_mov_b32 m0, s74
	ds_read_b128 v[214:217], v199 offset:32768
	ds_read_b128 v[218:221], v199 offset:33792
	ds_read_b128 v[222:225], v199 offset:34816
	ds_read_b128 v[226:229], v199 offset:35840
	ds_read_b128 v[230:233], v199 offset:36864
	ds_read_b128 v[234:237], v199 offset:37888
	ds_read_b128 v[238:241], v199 offset:38912
	ds_read_b128 v[242:245], v199 offset:39936
	global_load_lds_dwordx4 v152, s[10:11]
	s_mov_b32 m0, s75
	s_nop 0
	global_load_lds_dwordx4 v156, s[10:11]
	s_waitcnt vmcnt(8)
	s_waitcnt lgkmcnt(0)
	s_setprio 1
	s_barrier
	v_mfma_f32_16x16x32_bf16 v[112:115], v[148:151], v[214:217], v[112:115]
	v_mfma_f32_16x16x32_bf16 v[80:83], v[174:177], v[214:217], v[80:83]
	v_mfma_f32_16x16x32_bf16 v[116:119], v[148:151], v[222:225], v[116:119]
	v_mfma_f32_16x16x32_bf16 v[88:91], v[174:177], v[222:225], v[88:91]
	v_mfma_f32_16x16x32_bf16 v[124:127], v[148:151], v[230:233], v[124:127]
	v_mfma_f32_16x16x32_bf16 v[92:95], v[174:177], v[230:233], v[92:95]
	v_mfma_f32_16x16x32_bf16 v[120:123], v[148:151], v[238:241], v[120:123]
	v_mfma_f32_16x16x32_bf16 v[84:87], v[174:177], v[238:241], v[84:87]
	v_mfma_f32_16x16x32_bf16 v[112:115], v[170:173], v[218:221], v[112:115]
	v_mfma_f32_16x16x32_bf16 v[80:83], v[178:181], v[218:221], v[80:83]
	v_mfma_f32_16x16x32_bf16 v[116:119], v[170:173], v[226:229], v[116:119]
	v_mfma_f32_16x16x32_bf16 v[88:91], v[178:181], v[226:229], v[88:91]
	v_mfma_f32_16x16x32_bf16 v[124:127], v[170:173], v[234:237], v[124:127]
	v_mfma_f32_16x16x32_bf16 v[92:95], v[178:181], v[234:237], v[92:95]
	v_mfma_f32_16x16x32_bf16 v[120:123], v[170:173], v[242:245], v[120:123]
	v_mfma_f32_16x16x32_bf16 v[84:87], v[178:181], v[242:245], v[84:87]
	s_setprio 0
	s_setprio 1
	v_mfma_f32_16x16x32_bf16 v[108:111], v[182:185], v[214:217], v[108:111]
	v_mfma_f32_16x16x32_bf16 v[76:79], v[202:205], v[214:217], v[76:79]
	v_mfma_f32_16x16x32_bf16 v[104:107], v[182:185], v[222:225], v[104:107]
	v_mfma_f32_16x16x32_bf16 v[72:75], v[202:205], v[222:225], v[72:75]
	v_mfma_f32_16x16x32_bf16 v[100:103], v[182:185], v[230:233], v[100:103]
	v_mfma_f32_16x16x32_bf16 v[68:71], v[202:205], v[230:233], v[68:71]
	v_mfma_f32_16x16x32_bf16 v[96:99], v[182:185], v[238:241], v[96:99]
	v_mfma_f32_16x16x32_bf16 v[64:67], v[202:205], v[238:241], v[64:67]
	v_mfma_f32_16x16x32_bf16 v[108:111], v[186:189], v[218:221], v[108:111]
	v_mfma_f32_16x16x32_bf16 v[76:79], v[206:209], v[218:221], v[76:79]
	v_mfma_f32_16x16x32_bf16 v[104:107], v[186:189], v[226:229], v[104:107]
	v_mfma_f32_16x16x32_bf16 v[72:75], v[206:209], v[226:229], v[72:75]
	v_mfma_f32_16x16x32_bf16 v[100:103], v[186:189], v[234:237], v[100:103]
	v_mfma_f32_16x16x32_bf16 v[68:71], v[206:209], v[234:237], v[68:71]
	v_mfma_f32_16x16x32_bf16 v[96:99], v[186:189], v[242:245], v[96:99]
	v_mfma_f32_16x16x32_bf16 v[64:67], v[206:209], v[242:245], v[64:67]
	s_barrier
	s_setprio 0
	s_add_i32 s10, s16, s63
	s_mov_b32 m0, s10
	ds_read_b128 v[214:217], v199 offset:49152
	ds_read_b128 v[218:221], v199 offset:50176
	ds_read_b128 v[222:225], v199 offset:51200
	ds_read_b128 v[226:229], v199 offset:52224
	ds_read_b128 v[230:233], v199 offset:53248
	ds_read_b128 v[234:237], v199 offset:54272
	ds_read_b128 v[238:241], v199 offset:55296
	ds_read_b128 v[242:245], v199 offset:56320
	global_load_lds_dwordx4 v154, s[98:99]
	s_add_i32 m0, s10, 0x2000
	s_add_u32 s8, s8, 0x80080
	s_addc_u32 s9, s9, 0
	s_add_i32 s10, s17, s63
	global_load_lds_dwordx4 v158, s[98:99]
	s_mov_b32 m0, s10
	s_nop 0
	global_load_lds_dwordx4 v154, s[8:9]
	s_add_i32 m0, s10, 0x2000
	s_nop 0
	global_load_lds_dwordx4 v158, s[8:9]
	s_mov_b32 m0, s82
	s_nop 0
	global_load_lds_dwordx4 v152, s[100:101]
	s_mov_b32 m0, s83
	s_nop 0
	global_load_lds_dwordx4 v156, s[100:101]
	s_waitcnt vmcnt(8)
	s_waitcnt lgkmcnt(0)
	s_setprio 1
	s_barrier
	v_mfma_f32_16x16x32_bf16 v[48:51], v[148:151], v[214:217], v[48:51]
	v_mfma_f32_16x16x32_bf16 v[16:19], v[174:177], v[214:217], v[16:19]
	v_mfma_f32_16x16x32_bf16 v[52:55], v[148:151], v[222:225], v[52:55]
	v_mfma_f32_16x16x32_bf16 v[24:27], v[174:177], v[222:225], v[24:27]
	v_mfma_f32_16x16x32_bf16 v[60:63], v[148:151], v[230:233], v[60:63]
	v_mfma_f32_16x16x32_bf16 v[28:31], v[174:177], v[230:233], v[28:31]
	v_mfma_f32_16x16x32_bf16 v[56:59], v[148:151], v[238:241], v[56:59]
	v_mfma_f32_16x16x32_bf16 v[20:23], v[174:177], v[238:241], v[20:23]
	v_mfma_f32_16x16x32_bf16 v[48:51], v[170:173], v[218:221], v[48:51]
	v_mfma_f32_16x16x32_bf16 v[16:19], v[178:181], v[218:221], v[16:19]
	v_mfma_f32_16x16x32_bf16 v[52:55], v[170:173], v[226:229], v[52:55]
	v_mfma_f32_16x16x32_bf16 v[24:27], v[178:181], v[226:229], v[24:27]
	v_mfma_f32_16x16x32_bf16 v[60:63], v[170:173], v[234:237], v[60:63]
	v_mfma_f32_16x16x32_bf16 v[28:31], v[178:181], v[234:237], v[28:31]
	v_mfma_f32_16x16x32_bf16 v[56:59], v[170:173], v[242:245], v[56:59]
	v_mfma_f32_16x16x32_bf16 v[20:23], v[178:181], v[242:245], v[20:23]
	s_setprio 0
	s_setprio 1
	v_mfma_f32_16x16x32_bf16 v[44:47], v[182:185], v[214:217], v[44:47]
	v_mfma_f32_16x16x32_bf16 v[12:15], v[202:205], v[214:217], v[12:15]
	v_mfma_f32_16x16x32_bf16 v[40:43], v[182:185], v[222:225], v[40:43]
	v_mfma_f32_16x16x32_bf16 v[8:11], v[202:205], v[222:225], v[8:11]
	v_mfma_f32_16x16x32_bf16 v[36:39], v[182:185], v[230:233], v[36:39]
	v_mfma_f32_16x16x32_bf16 v[4:7], v[202:205], v[230:233], v[4:7]
	v_mfma_f32_16x16x32_bf16 v[32:35], v[182:185], v[238:241], v[32:35]
	v_mfma_f32_16x16x32_bf16 v[0:3], v[202:205], v[238:241], v[0:3]
	v_mfma_f32_16x16x32_bf16 v[44:47], v[186:189], v[218:221], v[44:47]
	v_mfma_f32_16x16x32_bf16 v[12:15], v[206:209], v[218:221], v[12:15]
	v_mfma_f32_16x16x32_bf16 v[40:43], v[186:189], v[226:229], v[40:43]
	v_mfma_f32_16x16x32_bf16 v[8:11], v[206:209], v[226:229], v[8:11]
	v_mfma_f32_16x16x32_bf16 v[36:39], v[186:189], v[234:237], v[36:39]
	v_mfma_f32_16x16x32_bf16 v[4:7], v[206:209], v[234:237], v[4:7]
	v_mfma_f32_16x16x32_bf16 v[32:35], v[186:189], v[242:245], v[32:35]
	v_mfma_f32_16x16x32_bf16 v[0:3], v[206:209], v[242:245], v[0:3]
	s_barrier
	s_setprio 0
	s_add_i32 s15, s15, 2
	s_add_u32 s6, s6, 0x100
	s_addc_u32 s7, s7, 0
	s_add_u32 s12, s12, 0x100
	s_addc_u32 s13, s13, 0
	s_cmp_gt_u32 s15, 29
